# attention tiles kt>=1: wave-uniform no-grow test branches straight off scc (m_new=m_run, alpha=1.0 by v_mov) instead of the max/cndmask/sub/exp chain
# baseline (speedup 1.0000x reference)
; #define LAS __attribute__((address_space(3)))
; __device__ __forceinline__ void attn_unit(const bf16* QB, const bf16* KN, const bf16* KR, const bf16* VT, bf16* YC, LAS unsigned char* lds, int b, int h, int u, int tid, int lane, int wave) {
;     ...
;         if (kt + 1 < nt_unit) { LAS unsigned char* nx = lds + ((kt + 1) & 1) * AT_STAGE;
; #pragma unroll
;             for (int i = 0; i < 2; ++i) { *(LAS u32x4*)(nx + kndst[i]) = kreg[i]; *(LAS u32x4*)(nx + vtdst[i]) = vreg[i]; }
;             *(LAS u32x4*)(nx + krdst) = kreg[2];
;             if (kt + 2 < nt_unit) { const unsigned t2 = (unsigned)(kt + 2) * 64u;
; #pragma unroll
;                 for (int i = 0; i < 2; ++i) { kreg[i] = *(const u32x4*)(KN + (knoff[i] + t2 * 512u)); vreg[i] = *(const u32x4*)(VT + (vtoff[i] + t2)); }
;                 kreg[2] = *(const u32x4*)(KR + (kroff + t2 * 64u)); }
;         }
;         LAS unsigned char* st = lds + (kt & 1) * AT_STAGE;
;         if (kt < nt_wave) {
;             f32x16 sa[2];
; #pragma unroll
;             for (int mt = 0; mt < 2; ++mt) {
; #pragma unroll
;                 for (int i = 0; i < 16; ++i) sa[mt][i] = 0.f;
; #pragma unroll
;                 for (int ks = 0; ks < 12; ++ks) { const bf16x8 af = *(const LAS bf16x8*)(st + (32 * mt + r32) * AT_KSTR + 32 * ks + 16 * hi);
;                     sa[mt] = __builtin_amdgcn_mfma_f32_32x32x16_bf16(af, qf[ks], sa[mt], 0, 0, 0); }
;             }
;             float mx = sa[0][0];
; #pragma unroll
;             for (int i = 1; i < 16; ++i) mx = fmaxf(mx, sa[0][i]);
; #pragma unroll
;             for (int i = 0; i < 16; ++i) mx = fmaxf(mx, sa[1][i]);
;             mx = fmaxf(mx, __shfl_xor(mx, 32));
;             const bool grow = __builtin_amdgcn_ballot_w64(mx - m_run > 8.0f) != 0ull;
;             const float m_new = grow ? fmaxf(m_run, mx) : m_run; const float alpha = grow ? __builtin_amdgcn_exp2f(m_run - m_new) : 1.0f; m_run = m_new;
;             float ls = 0.f;
; #pragma unroll
;             for (int mt = 0; mt < 2; ++mt)
; #pragma unroll
;                 for (int i = 0; i < 16; ++i) { const float p = __builtin_amdgcn_exp2f(sa[mt][i] - m_new); sa[mt][i] = p; ls += p; }
.LBB0_1470:
	s_add_i32 s6, s4, 1
	s_bitcmp1_b32 s6, 0
	s_cselect_b32 s5, 0xac00, 0
	s_add_i32 s28, s5, 0
	s_cmp_gt_i32 s4, s0
	s_cbranch_scc1 .Lattn_stage_only
	s_cmp_eq_u32 s6, 1
	s_cbranch_scc1 .Lattn_first
	s_bitcmp1_b32 s4, 0
	s_cselect_b32 s4, 0xac00, 0
	v_add_u32_e32 v208, s4, v199
	v_add_u32_e32 v72, v208, v194
	v_add_u32_e32 v230, v208, v195
	ds_read_b128 v[210:213], v72
	ds_read_b128 v[214:217], v72 offset:32
	ds_read_b128 v[218:221], v72 offset:64
	ds_read_b128 v[222:225], v72 offset:96
	s_waitcnt lgkmcnt(3)
	v_mfma_f32_32x32x16_bf16 v[80:95], v[210:213], v[140:143], 0
	ds_read_b128 v[226:229], v72 offset:128
	v_add_u32_e32 v64, s28, v170
	s_waitcnt vmcnt(4)
	ds_write_b128 v64, v[148:151]
	s_waitcnt lgkmcnt(4)
	v_mfma_f32_32x32x16_bf16 v[80:95], v[214:217], v[136:139], v[80:95]
	ds_read_b128 v[210:213], v72 offset:160
	v_add_u32_e32 v64, s28, v174
	s_waitcnt vmcnt(3)
	ds_write_b128 v64, v[144:147] offset:25600
	s_waitcnt lgkmcnt(5)
	v_mfma_f32_32x32x16_bf16 v[80:95], v[218:221], v[132:135], v[80:95]
	ds_read_b128 v[214:217], v72 offset:192
	v_add_u32_e32 v64, s28, v172
	s_waitcnt vmcnt(2)
	ds_write_b128 v64, v[156:159]
	s_waitcnt lgkmcnt(6)
	v_mfma_f32_32x32x16_bf16 v[80:95], v[222:225], v[128:131], v[80:95]
	ds_read_b128 v[218:221], v72 offset:224
	v_add_u32_e32 v64, s28, v176
	s_waitcnt vmcnt(1)
	ds_write_b128 v64, v[152:155] offset:25600
	s_waitcnt lgkmcnt(7)
	v_mfma_f32_32x32x16_bf16 v[80:95], v[226:229], v[124:127], v[80:95]
	ds_read_b128 v[222:225], v72 offset:256
	v_add_u32_e32 v64, s28, v192
	s_waitcnt vmcnt(0)
	ds_write_b128 v64, v[160:163] offset:256
	s_waitcnt lgkmcnt(7)
	v_mfma_f32_32x32x16_bf16 v[80:95], v[210:213], v[120:123], v[80:95]
	ds_read_b128 v[226:229], v72 offset:288
	v_lshl_add_u64 v[64:65], v[168:169], 1, s[62:63]
	global_load_dwordx4 v[148:151], v[64:65], off
	s_waitcnt lgkmcnt(6)
	v_mfma_f32_32x32x16_bf16 v[80:95], v[214:217], v[116:119], v[80:95]
	ds_read_b128 v[210:213], v72 offset:320
	v_add_u32_e32 v66, v188, v207
	v_mov_b32_e32 v67, v169
	v_lshl_add_u64 v[66:67], v[66:67], 1, s[48:49]
	global_load_dwordx4 v[144:147], v[66:67], off
	s_waitcnt lgkmcnt(5)
	v_mfma_f32_32x32x16_bf16 v[80:95], v[218:221], v[112:115], v[80:95]
	ds_read_b128 v[214:217], v72 offset:352
	v_mov_b32_e32 v185, v169
	v_lshl_add_u64 v[64:65], v[184:185], 1, s[62:63]
	global_load_dwordx4 v[156:159], v[64:65], off
	s_waitcnt lgkmcnt(4)
	v_mfma_f32_32x32x16_bf16 v[80:95], v[222:225], v[108:111], v[80:95]
	ds_read_b128 v[218:221], v230
	v_add_u32_e32 v66, v188, v206
	v_mov_b32_e32 v67, v169
	v_lshl_add_u64 v[66:67], v[66:67], 1, s[48:49]
	global_load_dwordx4 v[152:155], v[66:67], off
	s_waitcnt lgkmcnt(3)
	v_mfma_f32_32x32x16_bf16 v[80:95], v[226:229], v[104:107], v[80:95]
	ds_read_b128 v[222:225], v230 offset:32
	v_add_u32_e32 v64, v188, v181
	v_mov_b32_e32 v65, v169
	v_lshl_add_u64 v[64:65], v[64:65], 1, s[54:55]
	global_load_dwordx4 v[160:163], v[64:65], off
	s_waitcnt lgkmcnt(3)
	v_mfma_f32_32x32x16_bf16 v[80:95], v[210:213], v[100:103], v[80:95]
	ds_read_b128 v[226:229], v230 offset:64
	s_waitcnt lgkmcnt(3)
	v_mfma_f32_32x32x16_bf16 v[80:95], v[214:217], v[96:99], v[80:95]
	ds_read_b128 v[210:213], v230 offset:96
	s_waitcnt lgkmcnt(3)
	v_mfma_f32_32x32x16_bf16 v[64:79], v[218:221], v[140:143], 0
	ds_read_b128 v[214:217], v230 offset:128
	s_waitcnt lgkmcnt(3)
	v_mfma_f32_32x32x16_bf16 v[64:79], v[222:225], v[136:139], v[64:79]
	ds_read_b128 v[218:221], v230 offset:160
	s_waitcnt lgkmcnt(3)
	v_mfma_f32_32x32x16_bf16 v[64:79], v[226:229], v[132:135], v[64:79]
	ds_read_b128 v[222:225], v230 offset:192
	s_waitcnt lgkmcnt(3)
	v_mfma_f32_32x32x16_bf16 v[64:79], v[210:213], v[128:131], v[64:79]
	ds_read_b128 v[226:229], v230 offset:224
	v_max_f32_e32 v209, v80, v81
	v_max3_f32 v209, v209, v82, v83
	s_waitcnt lgkmcnt(3)
	v_mfma_f32_32x32x16_bf16 v[64:79], v[214:217], v[124:127], v[64:79]
	ds_read_b128 v[210:213], v230 offset:256
	v_max3_f32 v209, v209, v84, v85
	v_max3_f32 v209, v209, v86, v87
	s_waitcnt lgkmcnt(3)
	v_mfma_f32_32x32x16_bf16 v[64:79], v[218:221], v[120:123], v[64:79]
	ds_read_b128 v[214:217], v230 offset:288
	v_max3_f32 v209, v209, v88, v89
	v_max3_f32 v209, v209, v90, v91
	s_waitcnt lgkmcnt(3)
	v_mfma_f32_32x32x16_bf16 v[64:79], v[222:225], v[116:119], v[64:79]
	ds_read_b128 v[218:221], v230 offset:320
	v_max3_f32 v209, v209, v92, v93
	v_max3_f32 v209, v209, v94, v95
	s_waitcnt lgkmcnt(3)
	v_mfma_f32_32x32x16_bf16 v[64:79], v[226:229], v[112:115], v[64:79]
	ds_read_b128 v[222:225], v230 offset:352
	v_add_u32_e32 v226, v208, v196
	v_add_u32_e32 v227, v208, v197
	v_add_u32_e32 v228, v208, v198
	v_sub_f32_e32 v80, v80, v186
	v_exp_f32_e32 v80, v80
	s_waitcnt lgkmcnt(3)
	v_mfma_f32_32x32x16_bf16 v[64:79], v[210:213], v[108:111], v[64:79]
	ds_read_b128 v[210:213], v226 offset:25600
	v_sub_f32_e32 v81, v81, v186
	v_exp_f32_e32 v81, v81
	v_sub_f32_e32 v82, v82, v186
	v_exp_f32_e32 v82, v82
	s_waitcnt lgkmcnt(3)
	v_mfma_f32_32x32x16_bf16 v[64:79], v[214:217], v[104:107], v[64:79]
	ds_read_b128 v[214:217], v227 offset:25600
	v_sub_f32_e32 v83, v83, v186
	v_exp_f32_e32 v83, v83
	v_sub_f32_e32 v84, v84, v186
	v_exp_f32_e32 v84, v84
	s_waitcnt lgkmcnt(3)
	v_mfma_f32_32x32x16_bf16 v[64:79], v[218:221], v[100:103], v[64:79]
	ds_read_b128 v[218:221], v226 offset:34816
	v_sub_f32_e32 v85, v85, v186
	v_exp_f32_e32 v85, v85
	v_sub_f32_e32 v86, v86, v186
	v_exp_f32_e32 v86, v86
	s_waitcnt lgkmcnt(3)
	v_mfma_f32_32x32x16_bf16 v[64:79], v[222:225], v[96:99], v[64:79]
	ds_read_b128 v[222:225], v228 offset:25600
	v_sub_f32_e32 v87, v87, v186
	v_exp_f32_e32 v87, v87
	v_sub_f32_e32 v88, v88, v186
	v_exp_f32_e32 v88, v88
	v_sub_f32_e32 v89, v89, v186
	v_exp_f32_e32 v89, v89
	v_sub_f32_e32 v90, v90, v186
	v_exp_f32_e32 v90, v90
	v_sub_f32_e32 v91, v91, v186
	v_exp_f32_e32 v91, v91
	v_sub_f32_e32 v92, v92, v186
	v_exp_f32_e32 v92, v92
	v_sub_f32_e32 v93, v93, v186
	v_exp_f32_e32 v93, v93
	v_sub_f32_e32 v94, v94, v186
	v_exp_f32_e32 v94, v94
	v_sub_f32_e32 v95, v95, v186
	v_exp_f32_e32 v95, v95
	v_max3_f32 v185, v209, v64, v65
	v_max3_f32 v185, v185, v66, v67
	v_max3_f32 v185, v185, v68, v69
	v_max3_f32 v185, v185, v70, v71
	v_max3_f32 v185, v185, v72, v73
	v_max3_f32 v185, v185, v74, v75
	v_max3_f32 v185, v185, v76, v77
	v_max3_f32 v185, v185, v78, v79
	v_mov_b32_e32 v209, v185
	s_nop 1
	v_permlane32_swap_b32_e32 v209, v185
	s_nop 0
	v_max_f32_e32 v209, v209, v209
	v_max_f32_e32 v185, v185, v209
	v_sub_f32_e32 v209, v185, v186
	v_cmp_lt_f32_e32 vcc, s72, v209
	s_cmp_eq_u64 vcc, 0
	s_cselect_b64 s[4:5], -1, 0
	s_cbranch_scc1 .Lattn_keepmax
; __device__ __forceinline__ void attn_unit(const bf16* QB, const bf16* KN, const bf16* KR, const bf16* VT, bf16* YC, LAS unsigned char* lds, int b, int h, int u, int tid, int lane, int wave) {
;     ...
;             const bool grow = __builtin_amdgcn_ballot_w64(mx - m_run > 8.0f) != 0ull;
;             const float m_new = grow ? fmaxf(m_run, mx) : m_run; const float alpha = grow ? __builtin_amdgcn_exp2f(m_run - m_new) : 1.0f; m_run = m_new;
;             float ls = 0.f;
; #pragma unroll
;             for (int mt = 0; mt < 2; ++mt)
; #pragma unroll
;                 for (int i = 0; i < 16; ++i) { const float p = __builtin_amdgcn_exp2f(sa[mt][i] - m_new); sa[mt][i] = p; ls += p; }
;             l_run = l_run * alpha + ls;
;             if (grow) {
; #pragma unroll
;                 for (int d = 0; d < 4; ++d)
; #pragma unroll
;                     for (int i = 0; i < 16; ++i) ot[d][i] *= alpha;
;             }
	v_max_f32_e32 v209, v186, v186
	v_max_f32_e32 v185, v209, v185
	v_sub_f32_e32 v186, v186, v185
	v_exp_f32_e32 v186, v186
	s_nop 0
	v_pk_mul_f32 v[62:63], v[62:63], v[186:187] op_sel_hi:[1,0]
	v_pk_mul_f32 v[60:61], v[60:61], v[186:187] op_sel_hi:[1,0]
	v_pk_mul_f32 v[58:59], v[58:59], v[186:187] op_sel_hi:[1,0]
	v_pk_mul_f32 v[56:57], v[56:57], v[186:187] op_sel_hi:[1,0]
	v_pk_mul_f32 v[54:55], v[54:55], v[186:187] op_sel_hi:[1,0]
	v_pk_mul_f32 v[52:53], v[52:53], v[186:187] op_sel_hi:[1,0]
	v_pk_mul_f32 v[50:51], v[50:51], v[186:187] op_sel_hi:[1,0]
	v_pk_mul_f32 v[48:49], v[48:49], v[186:187] op_sel_hi:[1,0]
	v_pk_mul_f32 v[46:47], v[46:47], v[186:187] op_sel_hi:[1,0]
	v_pk_mul_f32 v[44:45], v[44:45], v[186:187] op_sel_hi:[1,0]
	v_pk_mul_f32 v[42:43], v[42:43], v[186:187] op_sel_hi:[1,0]
	v_pk_mul_f32 v[40:41], v[40:41], v[186:187] op_sel_hi:[1,0]
	v_pk_mul_f32 v[38:39], v[38:39], v[186:187] op_sel_hi:[1,0]
	v_pk_mul_f32 v[36:37], v[36:37], v[186:187] op_sel_hi:[1,0]
	v_pk_mul_f32 v[34:35], v[34:35], v[186:187] op_sel_hi:[1,0]
	v_pk_mul_f32 v[32:33], v[32:33], v[186:187] op_sel_hi:[1,0]
	v_pk_mul_f32 v[30:31], v[30:31], v[186:187] op_sel_hi:[1,0]
	v_pk_mul_f32 v[28:29], v[28:29], v[186:187] op_sel_hi:[1,0]
	v_pk_mul_f32 v[26:27], v[26:27], v[186:187] op_sel_hi:[1,0]
	v_pk_mul_f32 v[24:25], v[24:25], v[186:187] op_sel_hi:[1,0]
	v_pk_mul_f32 v[22:23], v[22:23], v[186:187] op_sel_hi:[1,0]
	v_pk_mul_f32 v[20:21], v[20:21], v[186:187] op_sel_hi:[1,0]
	v_pk_mul_f32 v[18:19], v[18:19], v[186:187] op_sel_hi:[1,0]
	v_pk_mul_f32 v[16:17], v[16:17], v[186:187] op_sel_hi:[1,0]
	v_pk_mul_f32 v[14:15], v[14:15], v[186:187] op_sel_hi:[1,0]
	v_pk_mul_f32 v[12:13], v[12:13], v[186:187] op_sel_hi:[1,0]
	v_pk_mul_f32 v[10:11], v[10:11], v[186:187] op_sel_hi:[1,0]
	v_pk_mul_f32 v[8:9], v[8:9], v[186:187] op_sel_hi:[1,0]
	v_pk_mul_f32 v[6:7], v[6:7], v[186:187] op_sel_hi:[1,0]
	v_pk_mul_f32 v[4:5], v[4:5], v[186:187] op_sel_hi:[1,0]
	v_pk_mul_f32 v[2:3], v[2:3], v[186:187] op_sel_hi:[1,0]
	v_pk_mul_f32 v[0:1], v[0:1], v[186:187] op_sel_hi:[1,0]
	v_pk_mul_f32 v[80:81], v[80:81], v[186:187] op_sel_hi:[1,0]
	v_pk_mul_f32 v[82:83], v[82:83], v[186:187] op_sel_hi:[1,0]
	v_pk_mul_f32 v[84:85], v[84:85], v[186:187] op_sel_hi:[1,0]
	v_pk_mul_f32 v[86:87], v[86:87], v[186:187] op_sel_hi:[1,0]
	v_pk_mul_f32 v[88:89], v[88:89], v[186:187] op_sel_hi:[1,0]
	v_pk_mul_f32 v[90:91], v[90:91], v[186:187] op_sel_hi:[1,0]
	v_pk_mul_f32 v[92:93], v[92:93], v[186:187] op_sel_hi:[1,0]
	v_pk_mul_f32 v[94:95], v[94:95], v[186:187] op_sel_hi:[1,0]
	s_branch .Lattn_nogrow
.Lattn_keepmax:
	v_mov_b32_e32 v185, v186
	v_mov_b32_e32 v186, 1.0
